# P1 gemm epilogue stores made write-through (sc1) so the grid barrier after it has less dirty L2 to write back
# speedup vs baseline: 1.0008x; 1.0008x over previous
; __device__ __forceinline__ unsigned cvt_pk_bf16(float lo, float hi) { unsigned r; asm volatile("v_cvt_pk_bf16_f32 %0, %1, %2" : "=v"(r) : "v"(lo), "v"(hi)); return r; }
;     __device__ __forceinline__ void operator()(const f32x4 (&acc)[2][2][4][2], const Unit& u, int wr, int wc, int fr, int fq) const {
;         const int row0 = u.pm * BM + wr * 64 + fr; const int col0 = u.pn * BM + wc * 32 + 8 * fq;
; #pragma unroll
;         for (int ai = 0; ai < 2; ++ai)
; #pragma unroll
;             for (int m = 0; m < 4; ++m) { bf16_t* rowp = O + (size_t)(row0 + ai * HALF + m * 16) * ldc + col0;
; #pragma unroll
;                 for (int bj = 0; bj < 2; ++bj) { const f32x4 v0 = acc[ai][bj][m][0], v1 = acc[ai][bj][m][1];
;                     u32x4 w; w.x = cvt_pk_bf16(v0[0], v0[1]); w.y = cvt_pk_bf16(v0[2], v0[3]); w.z = cvt_pk_bf16(v1[0], v1[1]); w.w = cvt_pk_bf16(v1[2], v1[3]);
;                     *(u32x4*)(rowp + bj * HALF) = w; } }
.LBB0_60:
	v_lshl_or_b32 v146, s54, 8, v151
	v_lshl_add_u32 v155, s26, 8, v149
	v_ashrrev_i32_e32 v147, 31, v146
	v_mov_b64_e32 v[144:145], s[10:11]
	v_mad_i64_i32 v[156:157], s[16:17], v155, s51, v[144:145]
	v_lshlrev_b64 v[146:147], 1, v[146:147]
	v_lshl_add_u64 v[156:157], v[156:157], 0, v[146:147]
	v_cvt_pk_bf16_f32 v124, v124, v125
	v_cvt_pk_bf16_f32 v125, v126, v127
	v_cvt_pk_bf16_f32 v126, v120, v121
	v_cvt_pk_bf16_f32 v127, v122, v123
	global_store_dwordx4 v[156:157], v[124:127], off sc1
	v_cvt_pk_bf16_f32 v112, v112, v113
	v_cvt_pk_bf16_f32 v113, v114, v115
	v_cvt_pk_bf16_f32 v114, v104, v105
	v_or_b32_e32 v104, 16, v155
	v_mad_i64_i32 v[104:105], s[16:17], v104, s51, v[144:145]
	v_cvt_pk_bf16_f32 v115, v106, v107
	global_store_dwordx4 v[156:157], v[112:115], off offset:256 sc1
	s_andn2_b64 vcc, exec, s[4:5]
	s_mov_b64 s[4:5], -1
	v_lshl_add_u64 v[112:113], v[104:105], 0, v[146:147]
	v_cvt_pk_bf16_f32 v104, v116, v117
	v_cvt_pk_bf16_f32 v105, v118, v119
	v_cvt_pk_bf16_f32 v106, v108, v109
	v_cvt_pk_bf16_f32 v107, v110, v111
	global_store_dwordx4 v[112:113], v[104:107], off sc1
	v_cvt_pk_bf16_f32 v96, v96, v97
	v_cvt_pk_bf16_f32 v97, v98, v99
	v_cvt_pk_bf16_f32 v98, v88, v89
	v_or_b32_e32 v88, 32, v155
	v_mad_i64_i32 v[88:89], s[16:17], v88, s51, v[144:145]
	v_cvt_pk_bf16_f32 v99, v90, v91
	global_store_dwordx4 v[112:113], v[96:99], off offset:256 sc1
	s_nop 1
	v_lshl_add_u64 v[96:97], v[88:89], 0, v[146:147]
	v_cvt_pk_bf16_f32 v88, v100, v101
	v_cvt_pk_bf16_f32 v89, v102, v103
	v_cvt_pk_bf16_f32 v90, v92, v93
	v_cvt_pk_bf16_f32 v91, v94, v95
	global_store_dwordx4 v[96:97], v[88:91], off sc1
	v_cvt_pk_bf16_f32 v80, v80, v81
	v_cvt_pk_bf16_f32 v81, v82, v83
	v_cvt_pk_bf16_f32 v82, v72, v73
	v_or_b32_e32 v72, 48, v155
	v_mad_i64_i32 v[72:73], s[16:17], v72, s51, v[144:145]
	v_cvt_pk_bf16_f32 v83, v74, v75
	global_store_dwordx4 v[96:97], v[80:83], off offset:256 sc1
	s_nop 1
	v_lshl_add_u64 v[80:81], v[72:73], 0, v[146:147]
	v_cvt_pk_bf16_f32 v72, v84, v85
	v_cvt_pk_bf16_f32 v73, v86, v87
	v_cvt_pk_bf16_f32 v74, v76, v77
	v_cvt_pk_bf16_f32 v75, v78, v79
	global_store_dwordx4 v[80:81], v[72:75], off sc1
	v_cvt_pk_bf16_f32 v68, v68, v69
	v_cvt_pk_bf16_f32 v69, v70, v71
	v_cvt_pk_bf16_f32 v70, v64, v65
	v_add_u32_e32 v64, 0x80, v155
	v_mad_i64_i32 v[64:65], s[16:17], v64, s51, v[144:145]
	v_lshl_add_u64 v[64:65], v[64:65], 0, v[146:147]
	v_cvt_pk_bf16_f32 v71, v66, v67
	global_store_dwordx4 v[80:81], v[68:71], off offset:256 sc1
	v_cvt_pk_bf16_f32 v60, v60, v61
	v_cvt_pk_bf16_f32 v61, v62, v63
	v_cvt_pk_bf16_f32 v62, v56, v57
	v_cvt_pk_bf16_f32 v63, v58, v59
	global_store_dwordx4 v[64:65], v[60:63], off sc1
	v_cvt_pk_bf16_f32 v48, v48, v49
	v_cvt_pk_bf16_f32 v49, v50, v51
	v_cvt_pk_bf16_f32 v50, v40, v41
	v_add_u32_e32 v40, 0x90, v155
	v_mad_i64_i32 v[40:41], s[16:17], v40, s51, v[144:145]
	v_cvt_pk_bf16_f32 v51, v42, v43
	global_store_dwordx4 v[64:65], v[48:51], off offset:256 sc1
	s_nop 1
	v_lshl_add_u64 v[48:49], v[40:41], 0, v[146:147]
	v_cvt_pk_bf16_f32 v40, v52, v53
	v_cvt_pk_bf16_f32 v41, v54, v55
	v_cvt_pk_bf16_f32 v42, v44, v45
	v_cvt_pk_bf16_f32 v43, v46, v47
	global_store_dwordx4 v[48:49], v[40:43], off sc1
	v_cvt_pk_bf16_f32 v32, v32, v33
	v_cvt_pk_bf16_f32 v33, v34, v35
	v_cvt_pk_bf16_f32 v34, v24, v25
	v_add_u32_e32 v24, 0xa0, v155
	v_mad_i64_i32 v[24:25], s[16:17], v24, s51, v[144:145]
	v_cvt_pk_bf16_f32 v35, v26, v27
	global_store_dwordx4 v[48:49], v[32:35], off offset:256 sc1
	s_nop 1
	v_lshl_add_u64 v[32:33], v[24:25], 0, v[146:147]
	v_cvt_pk_bf16_f32 v24, v36, v37
	v_cvt_pk_bf16_f32 v25, v38, v39
	v_cvt_pk_bf16_f32 v26, v28, v29
	v_cvt_pk_bf16_f32 v27, v30, v31
	global_store_dwordx4 v[32:33], v[24:27], off sc1
	v_cvt_pk_bf16_f32 v16, v16, v17
	v_cvt_pk_bf16_f32 v17, v18, v19
	v_cvt_pk_bf16_f32 v18, v8, v9
	v_add_u32_e32 v8, 0xb0, v155
	v_mad_i64_i32 v[8:9], s[16:17], v8, s51, v[144:145]
	v_cvt_pk_bf16_f32 v19, v10, v11
	global_store_dwordx4 v[32:33], v[16:19], off offset:256 sc1
	s_nop 1
	v_lshl_add_u64 v[16:17], v[8:9], 0, v[146:147]
	v_cvt_pk_bf16_f32 v8, v20, v21
	v_cvt_pk_bf16_f32 v9, v22, v23
	v_cvt_pk_bf16_f32 v10, v12, v13
	v_cvt_pk_bf16_f32 v11, v14, v15
	global_store_dwordx4 v[16:17], v[8:11], off sc1
	v_cvt_pk_bf16_f32 v4, v4, v5
	v_cvt_pk_bf16_f32 v5, v6, v7
	v_cvt_pk_bf16_f32 v6, v0, v1
	v_cvt_pk_bf16_f32 v7, v2, v3
	global_store_dwordx4 v[16:17], v[4:7], off offset:256 sc1
	s_cbranch_vccnz .LBB0_53
	s_andn2_b64 vcc, exec, s[8:9]
	s_cbranch_vccnz .LBB0_52
	s_barrier
	s_branch .LBB0_52
